# operand prep stores write-through (sc1) and late tiles publish their flag without an L2 writeback
# speedup vs baseline: 1.0076x; 1.0076x over previous
; __device__ __forceinline__ void p2_rwprep_tile(Frame& F, const Args& a, int t0) {
;     ...
;     for (int q = 0; q < 4; ++q) { const int hh = q >> 1, rb = q & 1; rw_chunk_prep(a, 2 * F.wave + hh, t0 + rb * 16, TD + rb * 16 * 64, DA + rb * 16 * 64, lw_, F.lane); }
;     __syncthreads();
; }
.LBB0_322:
	s_waitcnt vmcnt(0)
	s_barrier
	s_cmp_lg_u32 s98, 1
	s_cbranch_scc1 .Lrw_step
	s_cmp_lg_u32 s92, 0
	s_cbranch_scc1 .Lrw_step
	s_nop 0
	s_nop 0
	s_lshl_b32 s101, s56, 2
	s_add_i32 s101, s101, 0x8000
	v_mov_b32_e32 v204, s101
	v_mov_b32_e32 v205, 1
	s_mov_b64 exec, 1
	global_atomic_add v204, v205, s[90:91]
	s_mov_b64 exec, -1

; __device__ __forceinline__ f32x4 bf4(v2u u) { return (f32x4){bflo(u.x), bfhi(u.x), bflo(u.y), bfhi(u.y)}; }
; __device__ __forceinline__ void rw_chunk_prep(const Args& a, int head, int tc0, const LAS bf16* TDr, const LAS bf16* DAr, LAS unsigned char* lw_, int lane) {
;     ...
;         for (int i = 0; i < 4; ++i) {
;             const int tt = tt0 + i;
;             const f32x4 zr = bf4(*(const v2u*)(ZA + (size_t)tt * 3072 + cbase)), zk = bf4(*(const v2u*)(ZA + (size_t)tt * 3072 + 1024 + cbase)), zv = bf4(*(const v2u*)(ZA + (size_t)tt * 3072 + 2048 + cbase));
;             const f32x4 r = zr + (pr - zr) * mur, k = zk + (pk - zk) * muk, v = zv + (pv - zv) * muv;
;             pr = zr; pk = zk; pv = zv;
;             f32x4 lwv, alr;
; #pragma unroll
;             for (int cb = 0; cb < 4; ++cb) { const float x = -(w0[cb] + accw[cb][i]); const float sp = fmaxf(x, 0.f) + __logf(1.f + __expf(-fabsf(x))); lwv[cb] = -__expf(-sp - 0.5f); alr[cb] = __builtin_amdgcn_rcpf(1.f + __expf(-(a0[cb] + acca[cb][i]))); }
;             const f32x4 kkr = k * kkw, kmod = k * (1.f + (alr - 1.f) * kaw);
;             float ssq = (kkr.x * kkr.x + kkr.y * kkr.y) + (kkr.z * kkr.z + kkr.w * kkr.w);
;             const f32x4 rkk = r * kmod * rkw; float rkp = (rkk.x + rkk.y) + (rkk.z + rkk.w);
;             ssq = row16_sum(ssq); rkp = row16_sum(rkp);
;             const float inv = __builtin_amdgcn_rsqf(fmaxf(ssq, 1e-24f));
;             const f32x4 kk = kkr * inv;
;             rr[i] = r; km[i] = kmod; av[i] = -kk; bv[i] = kk * alr; lw[i] = lwv; vv[i] = v;
;             if (j == 0) RK[(size_t)tt * 16 + head] = rkp;
.LBB0_335:
	s_or_b64 exec, exec, s[2:3]
	v_mov_b64_e32 v[96:97], s[72:73]
	v_mad_i64_i32 v[96:97], s[2:3], v106, s44, v[96:97]
	v_lshl_add_u64 v[96:97], v[96:97], 0, v[66:67]
	global_load_dwordx2 v[108:109], v[96:97], off
	global_load_dwordx2 v[110:111], v[96:97], off offset:2048
	v_add_co_u32_e32 v96, vcc, s45, v96
	s_waitcnt vmcnt(8)
	v_add_f32_e32 v107, v24, v60
	v_addc_co_u32_e32 v97, vcc, 0, v97, vcc
	global_load_dwordx2 v[96:97], v[96:97], off
	v_mov_b32_e32 v230, s45
	v_mov_b32_e32 v231, 0
	v_or_b32_e32 v224, 1, v106
	v_mov_b64_e32 v[226:227], s[72:73]
	v_mad_i64_i32 v[226:227], s[2:3], v224, s44, v[226:227]
	v_lshl_add_u64 v[226:227], v[226:227], 0, v[66:67]
	v_lshl_add_u64 v[228:229], v[226:227], 0, v[230:231]
	global_load_dwordx2 v[206:207], v[226:227], off
	global_load_dwordx2 v[208:209], v[226:227], off offset:2048
	global_load_dwordx2 v[210:211], v[228:229], off
	v_or_b32_e32 v224, 2, v106
	v_mov_b64_e32 v[232:233], s[72:73]
	v_mad_i64_i32 v[232:233], s[2:3], v224, s44, v[232:233]
	v_lshl_add_u64 v[232:233], v[232:233], 0, v[66:67]
	v_lshl_add_u64 v[234:235], v[232:233], 0, v[230:231]
	global_load_dwordx2 v[212:213], v[232:233], off
	global_load_dwordx2 v[214:215], v[232:233], off offset:2048
	global_load_dwordx2 v[216:217], v[234:235], off
	v_or_b32_e32 v224, 3, v106
	v_mov_b64_e32 v[238:239], s[72:73]
	v_mad_i64_i32 v[238:239], s[2:3], v224, s44, v[238:239]
	v_lshl_add_u64 v[238:239], v[238:239], 0, v[66:67]
	v_lshl_add_u64 v[240:241], v[238:239], 0, v[230:231]
	global_load_dwordx2 v[218:219], v[238:239], off
	global_load_dwordx2 v[220:221], v[238:239], off offset:2048
	global_load_dwordx2 v[222:223], v[240:241], off
	v_add_f32_e32 v28, v28, v61
	v_add_f32_e32 v32, v32, v62
	v_add_f32_e32 v56, v56, v63
	v_mul_f32_e32 v107, 0xbfb8aa3b, v107
	v_mul_f32_e32 v28, 0xbfb8aa3b, v28
	v_mul_f32_e32 v32, 0xbfb8aa3b, v32
	v_mul_f32_e32 v56, 0xbfb8aa3b, v56
	v_exp_f32_e32 v107, v107
	v_exp_f32_e32 v28, v28
	v_exp_f32_e32 v32, v32
	v_exp_f32_e32 v56, v56
	v_add_f32_e32 v107, 1.0, v107
	v_add_f32_e32 v28, 1.0, v28
	v_add_f32_e32 v32, 1.0, v32
	v_add_f32_e32 v56, 1.0, v56
	v_rcp_f32_e32 v112, v107
	v_rcp_f32_e32 v114, v32
	v_rcp_f32_e32 v115, v56
	v_rcp_f32_e32 v113, v28
	s_lshl_b64 s[2:3], s[0:1], 2
	v_mov_b32_e32 v190, v67
	v_pk_add_f32 v[116:117], v[114:115], -1.0 op_sel_hi:[1,0]
	v_pk_add_f32 v[118:119], v[112:113], -1.0 op_sel_hi:[1,0]
	s_waitcnt vmcnt(16)
	v_pk_fma_f32 v[130:131], v[54:55], v[116:117], 1.0 op_sel_hi:[1,1,0]
	v_pk_fma_f32 v[128:129], v[52:53], v[118:119], 1.0 op_sel_hi:[1,1,0]
	v_mov_b32_e32 v24, v67
	s_add_u32 s26, s35, s2
	s_addc_u32 s27, s36, s3
	s_waitcnt vmcnt(11)
	v_lshlrev_b32_e32 v122, 16, v108
	v_and_b32_e32 v123, 0xffff0000, v108
	v_lshlrev_b32_e32 v124, 16, v109
	s_waitcnt vmcnt(10)
	v_lshlrev_b32_e32 v120, 16, v110
	v_and_b32_e32 v121, 0xffff0000, v110
	v_lshlrev_b32_e32 v126, 16, v111
	v_and_b32_e32 v127, 0xffff0000, v111
	v_and_b32_e32 v125, 0xffff0000, v109
	v_sub_f32_e32 v109, v100, v123
	v_sub_f32_e32 v108, v98, v122
	v_sub_f32_e32 v100, v99, v124
	v_sub_f32_e32 v99, v105, v127
	v_sub_f32_e32 v98, v104, v126
	v_sub_f32_e32 v103, v103, v121
	v_sub_f32_e32 v102, v102, v120
	v_sub_f32_e32 v101, v101, v125
	v_pk_fma_f32 v[102:103], v[48:49], v[102:103], v[120:121]
	v_pk_fma_f32 v[98:99], v[50:51], v[98:99], v[126:127]
	v_pk_fma_f32 v[110:111], v[46:47], v[100:101], v[124:125]
	v_pk_fma_f32 v[108:109], v[44:45], v[108:109], v[122:123]
	v_pk_mul_f32 v[118:119], v[38:39], v[98:99]
	v_pk_mul_f32 v[116:117], v[36:37], v[102:103]
	v_pk_mul_f32 v[100:101], v[130:131], v[98:99]
	v_pk_mul_f32 v[102:103], v[128:129], v[102:103]
	v_pk_mul_f32 v[98:99], v[118:119], v[118:119]
	v_pk_mul_f32 v[104:105], v[116:117], v[116:117]
	v_pk_mul_f32 v[128:129], v[108:109], v[102:103]
	v_pk_mul_f32 v[130:131], v[110:111], v[100:101]
	v_pk_mov_b32 v[132:133], v[104:105], v[98:99] op_sel:[1,0]
	v_mov_b32_e32 v105, v99
	v_pk_mul_f32 v[98:99], v[42:43], v[130:131]
	v_pk_mul_f32 v[128:129], v[40:41], v[128:129]
	v_pk_add_f32 v[104:105], v[132:133], v[104:105]
	v_add_f32_e32 v28, v128, v129
	v_add_f32_e32 v32, v98, v99
	v_add_f32_e32 v56, v104, v105
	v_add_f32_e32 v28, v28, v32
	s_nop 0
	v_add_f32_dpp v32, v56, v56 quad_perm:[1,0,3,2] row_mask:0xf bank_mask:0xf bound_ctrl:1
	v_add_f32_dpp v28, v28, v28 quad_perm:[1,0,3,2] row_mask:0xf bank_mask:0xf bound_ctrl:1
	s_nop 0
	v_add_f32_dpp v32, v32, v32 quad_perm:[2,3,0,1] row_mask:0xf bank_mask:0xf bound_ctrl:1
	v_add_f32_dpp v28, v28, v28 quad_perm:[2,3,0,1] row_mask:0xf bank_mask:0xf bound_ctrl:1
	s_nop 0
	v_add_f32_dpp v191, v32, v32 row_half_mirror row_mask:0xf bank_mask:0xf bound_ctrl:1
	v_add_f32_dpp v28, v28, v28 row_half_mirror row_mask:0xf bank_mask:0xf bound_ctrl:1
	s_nop 0
	v_mov_b32_dpp v190, v191 row_mirror row_mask:0xf bank_mask:0xf
	v_mov_b32_dpp v24, v28 row_mirror row_mask:0xf bank_mask:0xf
	s_and_saveexec_b64 s[2:3], s[24:25]
	s_cbranch_execz .LBB0_337
	v_ashrrev_i32_e32 v107, 31, v106
	v_lshlrev_b64 v[98:99], 6, v[106:107]
	v_lshl_add_u64 v[98:99], s[26:27], 0, v[98:99]
	v_add_f32_e32 v24, v28, v24
	global_store_dword v[98:99], v24, off sc1
; __device__ __forceinline__ f32x4 bf4(v2u u) { return (f32x4){bflo(u.x), bfhi(u.x), bflo(u.y), bfhi(u.y)}; }
; __device__ __forceinline__ void rw_chunk_prep(const Args& a, int head, int tc0, const LAS bf16* TDr, const LAS bf16* DAr, LAS unsigned char* lw_, int lane) {
;     ...
;         for (int i = 0; i < 4; ++i) {
;             const int tt = tt0 + i;
;             const f32x4 zr = bf4(*(const v2u*)(ZA + (size_t)tt * 3072 + cbase)), zk = bf4(*(const v2u*)(ZA + (size_t)tt * 3072 + 1024 + cbase)), zv = bf4(*(const v2u*)(ZA + (size_t)tt * 3072 + 2048 + cbase));
;             const f32x4 r = zr + (pr - zr) * mur, k = zk + (pk - zk) * muk, v = zv + (pv - zv) * muv;
;             pr = zr; pk = zk; pv = zv;
;             f32x4 lwv, alr;
; #pragma unroll
;             for (int cb = 0; cb < 4; ++cb) { const float x = -(w0[cb] + accw[cb][i]); const float sp = fmaxf(x, 0.f) + __logf(1.f + __expf(-fabsf(x))); lwv[cb] = -__expf(-sp - 0.5f); alr[cb] = __builtin_amdgcn_rcpf(1.f + __expf(-(a0[cb] + acca[cb][i]))); }
;             const f32x4 kkr = k * kkw, kmod = k * (1.f + (alr - 1.f) * kaw);
;             float ssq = (kkr.x * kkr.x + kkr.y * kkr.y) + (kkr.z * kkr.z + kkr.w * kkr.w);
;             const f32x4 rkk = r * kmod * rkw; float rkp = (rkk.x + rkk.y) + (rkk.z + rkk.w);
;             ssq = row16_sum(ssq); rkp = row16_sum(rkp);
;             const float inv = __builtin_amdgcn_rsqf(fmaxf(ssq, 1e-24f));
;             const f32x4 kk = kkr * inv;
;             rr[i] = r; km[i] = kmod; av[i] = -kk; bv[i] = kk * alr; lw[i] = lwv; vv[i] = v;
;             if (j == 0) RK[(size_t)tt * 16 + head] = rkp;
.LBB0_337:
	s_or_b64 exec, exec, s[2:3]
	v_or_b32_e32 v32, 1, v106
	v_mov_b64_e32 v[98:99], s[72:73]
	v_mad_i64_i32 v[98:99], s[2:3], v32, s44, v[98:99]
	v_lshl_add_u64 v[98:99], v[98:99], 0, v[66:67]
	s_waitcnt vmcnt(6)
	v_mov_b32_e32 v128, v206
	v_mov_b32_e32 v129, v207
	v_add_f32_e32 v24, v25, v60
	v_mul_f32_e32 v24, 0xbfb8aa3b, v24
	v_exp_f32_e32 v24, v24
	v_mov_b32_e32 v193, v67
	v_add_f32_e32 v24, 1.0, v24
	s_nop 0
	v_lshlrev_b32_e32 v104, 16, v128
	v_and_b32_e32 v105, 0xffff0000, v128
	v_lshlrev_b32_e32 v132, 16, v129
	v_and_b32_e32 v133, 0xffff0000, v129
	v_mov_b32_e32 v128, v208
	v_mov_b32_e32 v129, v209
	v_add_co_u32_e32 v98, vcc, s45, v98
	s_nop 0
	v_lshlrev_b32_e32 v134, 16, v128
	v_addc_co_u32_e32 v99, vcc, 0, v99, vcc
	v_mov_b32_e32 v98, v210
	v_mov_b32_e32 v99, v211
	v_and_b32_e32 v135, 0xffff0000, v128
	v_sub_f32_e32 v128, v122, v104
	v_sub_f32_e32 v122, v124, v132
	v_rcp_f32_e32 v124, v24
	v_add_f32_e32 v24, v29, v61
	v_mul_f32_e32 v24, 0xbfb8aa3b, v24
	v_exp_f32_e32 v24, v24
	v_lshlrev_b32_e32 v136, 16, v129
	v_and_b32_e32 v137, 0xffff0000, v129
	v_sub_f32_e32 v129, v123, v105
	v_add_f32_e32 v24, 1.0, v24
	v_sub_f32_e32 v123, v125, v133
	v_rcp_f32_e32 v125, v24
	v_add_f32_e32 v24, v33, v62
	v_mul_f32_e32 v24, 0xbfb8aa3b, v24
	v_exp_f32_e32 v24, v24
	v_sub_f32_e32 v130, v126, v136
	v_sub_f32_e32 v131, v127, v137
	v_sub_f32_e32 v139, v121, v135
	v_add_f32_e32 v24, 1.0, v24
	v_rcp_f32_e32 v126, v24
	v_add_f32_e32 v24, v57, v63
	v_mul_f32_e32 v24, 0xbfb8aa3b, v24
	v_exp_f32_e32 v24, v24
	v_sub_f32_e32 v138, v120, v134
	v_pk_fma_f32 v[28:29], v[48:49], v[138:139], v[134:135]
	v_pk_add_f32 v[138:139], v[124:125], -1.0 op_sel_hi:[1,0]
	v_add_f32_e32 v24, 1.0, v24
	v_rcp_f32_e32 v127, v24
	v_pk_fma_f32 v[24:25], v[50:51], v[130:131], v[136:137]
	v_pk_fma_f32 v[120:121], v[44:45], v[128:129], v[104:105]
	v_pk_mul_f32 v[128:129], v[38:39], v[24:25]
	v_pk_add_f32 v[56:57], v[126:127], -1.0 op_sel_hi:[1,0]
	v_pk_mul_f32 v[130:131], v[36:37], v[28:29]
	v_pk_fma_f32 v[138:139], v[52:53], v[138:139], 1.0 op_sel_hi:[1,1,0]
	v_pk_fma_f32 v[56:57], v[54:55], v[56:57], 1.0 op_sel_hi:[1,1,0]
	v_pk_mul_f32 v[28:29], v[138:139], v[28:29]
	v_pk_mul_f32 v[24:25], v[56:57], v[24:25]
	v_pk_mul_f32 v[56:57], v[128:129], v[128:129]
	v_pk_mul_f32 v[138:139], v[130:131], v[130:131]
	v_pk_fma_f32 v[122:123], v[46:47], v[122:123], v[132:133]
	v_pk_mov_b32 v[140:141], v[138:139], v[56:57] op_sel:[1,0]
	v_mov_b32_e32 v139, v57
	v_pk_add_f32 v[56:57], v[140:141], v[138:139]
	v_pk_mul_f32 v[138:139], v[122:123], v[24:25]
	v_add_f32_e32 v33, v56, v57
	v_pk_mul_f32 v[56:57], v[120:121], v[28:29]
	v_pk_mul_f32 v[138:139], v[42:43], v[138:139]
	v_pk_mul_f32 v[56:57], v[40:41], v[56:57]
	v_add_f32_dpp v33, v33, v33 quad_perm:[1,0,3,2] row_mask:0xf bank_mask:0xf bound_ctrl:1
	v_add_f32_e32 v56, v56, v57
	v_add_f32_e32 v57, v138, v139
	v_add_f32_e32 v56, v56, v57
	v_add_f32_dpp v33, v33, v33 quad_perm:[2,3,0,1] row_mask:0xf bank_mask:0xf bound_ctrl:1
	v_mov_b32_e32 v57, v67
	s_nop 0
	v_add_f32_dpp v192, v33, v33 row_half_mirror row_mask:0xf bank_mask:0xf bound_ctrl:1
	v_add_f32_dpp v33, v56, v56 quad_perm:[1,0,3,2] row_mask:0xf bank_mask:0xf bound_ctrl:1
	s_nop 0
	v_mov_b32_dpp v193, v192 row_mirror row_mask:0xf bank_mask:0xf
	v_add_f32_dpp v33, v33, v33 quad_perm:[2,3,0,1] row_mask:0xf bank_mask:0xf bound_ctrl:1
	s_nop 1
	v_add_f32_dpp v56, v33, v33 row_half_mirror row_mask:0xf bank_mask:0xf bound_ctrl:1
	s_nop 1
	v_mov_b32_dpp v57, v56 row_mirror row_mask:0xf bank_mask:0xf
	s_and_saveexec_b64 s[2:3], s[24:25]
	s_cbranch_execz .LBB0_339
	v_ashrrev_i32_e32 v33, 31, v32
	v_lshlrev_b64 v[32:33], 6, v[32:33]
	v_lshl_add_u64 v[32:33], s[26:27], 0, v[32:33]
	v_add_f32_e32 v56, v56, v57
	global_store_dword v[32:33], v56, off sc1
; __device__ __forceinline__ f32x4 bf4(v2u u) { return (f32x4){bflo(u.x), bfhi(u.x), bflo(u.y), bfhi(u.y)}; }
; __device__ __forceinline__ void rw_chunk_prep(const Args& a, int head, int tc0, const LAS bf16* TDr, const LAS bf16* DAr, LAS unsigned char* lw_, int lane) {
;     ...
;         for (int i = 0; i < 4; ++i) {
;             const int tt = tt0 + i;
;             const f32x4 zr = bf4(*(const v2u*)(ZA + (size_t)tt * 3072 + cbase)), zk = bf4(*(const v2u*)(ZA + (size_t)tt * 3072 + 1024 + cbase)), zv = bf4(*(const v2u*)(ZA + (size_t)tt * 3072 + 2048 + cbase));
;             const f32x4 r = zr + (pr - zr) * mur, k = zk + (pk - zk) * muk, v = zv + (pv - zv) * muv;
;             pr = zr; pk = zk; pv = zv;
;             f32x4 lwv, alr;
; #pragma unroll
;             for (int cb = 0; cb < 4; ++cb) { const float x = -(w0[cb] + accw[cb][i]); const float sp = fmaxf(x, 0.f) + __logf(1.f + __expf(-fabsf(x))); lwv[cb] = -__expf(-sp - 0.5f); alr[cb] = __builtin_amdgcn_rcpf(1.f + __expf(-(a0[cb] + acca[cb][i]))); }
;             const f32x4 kkr = k * kkw, kmod = k * (1.f + (alr - 1.f) * kaw);
;             float ssq = (kkr.x * kkr.x + kkr.y * kkr.y) + (kkr.z * kkr.z + kkr.w * kkr.w);
;             const f32x4 rkk = r * kmod * rkw; float rkp = (rkk.x + rkk.y) + (rkk.z + rkk.w);
;             ssq = row16_sum(ssq); rkp = row16_sum(rkp);
;             const float inv = __builtin_amdgcn_rsqf(fmaxf(ssq, 1e-24f));
;             const f32x4 kk = kkr * inv;
;             rr[i] = r; km[i] = kmod; av[i] = -kk; bv[i] = kk * alr; lw[i] = lwv; vv[i] = v;
;             if (j == 0) RK[(size_t)tt * 16 + head] = rkp;
.LBB0_339:
	s_or_b64 exec, exec, s[2:3]
	v_or_b32_e32 v152, 2, v106
	v_mov_b64_e32 v[32:33], s[72:73]
	v_mad_i64_i32 v[32:33], s[2:3], v152, s44, v[32:33]
	v_lshl_add_u64 v[32:33], v[32:33], 0, v[66:67]
	s_waitcnt vmcnt(3)
	v_mov_b32_e32 v56, v212
	v_mov_b32_e32 v57, v213
	v_add_f32_e32 v26, v26, v60
	v_mul_f32_e32 v26, 0xbfb8aa3b, v26
	v_exp_f32_e32 v26, v26
	s_nop 0
	v_lshlrev_b32_e32 v144, 16, v56
	v_and_b32_e32 v145, 0xffff0000, v56
	v_lshlrev_b32_e32 v146, 16, v57
	v_and_b32_e32 v147, 0xffff0000, v57
	v_mov_b32_e32 v56, v214
	v_mov_b32_e32 v57, v215
	v_add_co_u32_e32 v32, vcc, s45, v32
	v_add_f32_e32 v26, 1.0, v26
	s_nop 0
	v_addc_co_u32_e32 v33, vcc, 0, v33, vcc
	v_mov_b32_e32 v32, v216
	v_mov_b32_e32 v33, v217
	s_nop 0
	v_lshlrev_b32_e32 v150, 16, v57
	v_sub_f32_e32 v140, v136, v150
	v_rcp_f32_e32 v136, v26
	v_add_f32_e32 v26, v30, v61
	v_mul_f32_e32 v26, 0xbfb8aa3b, v26
	v_exp_f32_e32 v26, v26
	v_and_b32_e32 v151, 0xffff0000, v57
	v_sub_f32_e32 v141, v137, v151
	v_lshlrev_b32_e32 v148, 16, v56
	v_add_f32_e32 v26, 1.0, v26
	v_rcp_f32_e32 v137, v26
	v_add_f32_e32 v26, v34, v62
	v_mul_f32_e32 v26, 0xbfb8aa3b, v26
	v_exp_f32_e32 v26, v26
	v_and_b32_e32 v149, 0xffff0000, v56
	v_sub_f32_e32 v57, v105, v145
	v_sub_f32_e32 v56, v104, v144
	v_add_f32_e32 v26, 1.0, v26
	v_rcp_f32_e32 v138, v26
	v_add_f32_e32 v26, v58, v63
	v_mul_f32_e32 v26, 0xbfb8aa3b, v26
	v_exp_f32_e32 v26, v26
	v_sub_f32_e32 v105, v133, v147
	v_sub_f32_e32 v104, v132, v146
	v_sub_f32_e32 v143, v135, v149
	v_add_f32_e32 v26, 1.0, v26
	v_rcp_f32_e32 v139, v26
	v_sub_f32_e32 v142, v134, v148
	v_pk_fma_f32 v[134:135], v[46:47], v[104:105], v[146:147]
	v_pk_fma_f32 v[132:133], v[44:45], v[56:57], v[144:145]
	v_pk_fma_f32 v[104:105], v[48:49], v[142:143], v[148:149]
	v_pk_fma_f32 v[56:57], v[50:51], v[140:141], v[150:151]
	v_pk_add_f32 v[194:195], v[138:139], -1.0 op_sel_hi:[1,0]
	v_pk_add_f32 v[196:197], v[136:137], -1.0 op_sel_hi:[1,0]
	v_pk_mul_f32 v[140:141], v[38:39], v[56:57]
	v_pk_mul_f32 v[142:143], v[36:37], v[104:105]
	v_pk_fma_f32 v[196:197], v[52:53], v[196:197], 1.0 op_sel_hi:[1,1,0]
	v_pk_fma_f32 v[194:195], v[54:55], v[194:195], 1.0 op_sel_hi:[1,1,0]
	v_pk_mul_f32 v[104:105], v[196:197], v[104:105]
	v_pk_mul_f32 v[56:57], v[194:195], v[56:57]
	v_pk_mul_f32 v[194:195], v[140:141], v[140:141]
	v_pk_mul_f32 v[196:197], v[142:143], v[142:143]
	s_nop 0
	v_pk_mov_b32 v[198:199], v[196:197], v[194:195] op_sel:[1,0]
	v_mov_b32_e32 v197, v195
	v_pk_add_f32 v[194:195], v[198:199], v[196:197]
	v_pk_mul_f32 v[196:197], v[134:135], v[56:57]
	v_add_f32_e32 v26, v194, v195
	v_pk_mul_f32 v[194:195], v[132:133], v[104:105]
	v_pk_mul_f32 v[196:197], v[42:43], v[196:197]
	v_pk_mul_f32 v[194:195], v[40:41], v[194:195]
	v_add_f32_e32 v34, v196, v197
	v_add_f32_e32 v30, v194, v195
	v_add_f32_dpp v26, v26, v26 quad_perm:[1,0,3,2] row_mask:0xf bank_mask:0xf bound_ctrl:1
	v_add_f32_e32 v30, v30, v34
	v_mov_b32_e32 v195, v67
	v_add_f32_dpp v26, v26, v26 quad_perm:[2,3,0,1] row_mask:0xf bank_mask:0xf bound_ctrl:1
	s_nop 1
	v_add_f32_dpp v194, v26, v26 row_half_mirror row_mask:0xf bank_mask:0xf bound_ctrl:1
	v_add_f32_dpp v26, v30, v30 quad_perm:[1,0,3,2] row_mask:0xf bank_mask:0xf bound_ctrl:1
	v_mov_b32_e32 v30, v67
	v_mov_b32_dpp v195, v194 row_mirror row_mask:0xf bank_mask:0xf
	v_add_f32_dpp v26, v26, v26 quad_perm:[2,3,0,1] row_mask:0xf bank_mask:0xf bound_ctrl:1
	s_nop 1
	v_add_f32_dpp v26, v26, v26 row_half_mirror row_mask:0xf bank_mask:0xf bound_ctrl:1
	s_nop 1
	v_mov_b32_dpp v30, v26 row_mirror row_mask:0xf bank_mask:0xf
	s_and_saveexec_b64 s[2:3], s[24:25]
	s_cbranch_execz .LBB0_341
	v_ashrrev_i32_e32 v153, 31, v152
	v_lshlrev_b64 v[152:153], 6, v[152:153]
	v_lshl_add_u64 v[152:153], s[26:27], 0, v[152:153]
	v_add_f32_e32 v26, v26, v30
	global_store_dword v[152:153], v26, off sc1

; __device__ __forceinline__ f32x4 bf4(v2u u) { return (f32x4){bflo(u.x), bfhi(u.x), bflo(u.y), bfhi(u.y)}; }
; __device__ __forceinline__ void rw_chunk_prep(const Args& a, int head, int tc0, const LAS bf16* TDr, const LAS bf16* DAr, LAS unsigned char* lw_, int lane) {
;     ...
;         for (int i = 0; i < 4; ++i) {
;             const int tt = tt0 + i;
;             const f32x4 zr = bf4(*(const v2u*)(ZA + (size_t)tt * 3072 + cbase)), zk = bf4(*(const v2u*)(ZA + (size_t)tt * 3072 + 1024 + cbase)), zv = bf4(*(const v2u*)(ZA + (size_t)tt * 3072 + 2048 + cbase));
;             const f32x4 r = zr + (pr - zr) * mur, k = zk + (pk - zk) * muk, v = zv + (pv - zv) * muv;
;             pr = zr; pk = zk; pv = zv;
;             f32x4 lwv, alr;
; #pragma unroll
;             for (int cb = 0; cb < 4; ++cb) { const float x = -(w0[cb] + accw[cb][i]); const float sp = fmaxf(x, 0.f) + __logf(1.f + __expf(-fabsf(x))); lwv[cb] = -__expf(-sp - 0.5f); alr[cb] = __builtin_amdgcn_rcpf(1.f + __expf(-(a0[cb] + acca[cb][i]))); }
;             const f32x4 kkr = k * kkw, kmod = k * (1.f + (alr - 1.f) * kaw);
;             float ssq = (kkr.x * kkr.x + kkr.y * kkr.y) + (kkr.z * kkr.z + kkr.w * kkr.w);
;             const f32x4 rkk = r * kmod * rkw; float rkp = (rkk.x + rkk.y) + (rkk.z + rkk.w);
;             ssq = row16_sum(ssq); rkp = row16_sum(rkp);
;             const float inv = __builtin_amdgcn_rsqf(fmaxf(ssq, 1e-24f));
;             const f32x4 kk = kkr * inv;
;             rr[i] = r; km[i] = kmod; av[i] = -kk; bv[i] = kk * alr; lw[i] = lwv; vv[i] = v;
;             if (j == 0) RK[(size_t)tt * 16 + head] = rkp;
.Lrw_t3_go:
	v_mov_b32_e32 v198, v218
	v_mov_b32_e32 v199, v219
	v_mov_b32_e32 v200, v220
	v_mov_b32_e32 v201, v221
	v_add_co_u32_e32 v106, vcc, s45, v106
	v_add_f32_e32 v26, v27, v60
	s_nop 0
	v_addc_co_u32_e32 v107, vcc, 0, v107, vcc
	v_mov_b32_e32 v106, v222
	v_mov_b32_e32 v107, v223
	v_add_f32_e32 v27, v31, v61
	v_add_f32_e32 v30, v35, v62
	v_add_f32_e32 v31, v59, v63
	v_mul_f32_e32 v26, 0xbfb8aa3b, v26
	v_mul_f32_e32 v27, 0xbfb8aa3b, v27
	v_mul_f32_e32 v30, 0xbfb8aa3b, v30
	v_mul_f32_e32 v31, 0xbfb8aa3b, v31
	v_exp_f32_e32 v26, v26
	v_exp_f32_e32 v27, v27
	v_exp_f32_e32 v30, v30
	v_exp_f32_e32 v31, v31
	v_add_f32_e32 v26, 1.0, v26
	v_add_f32_e32 v27, 1.0, v27
	v_add_f32_e32 v30, 1.0, v30
	v_add_f32_e32 v31, 1.0, v31
	v_rcp_f32_e32 v58, v26
	v_rcp_f32_e32 v34, v30
	v_rcp_f32_e32 v35, v31
	v_rcp_f32_e32 v59, v27
	v_mov_b32_e32 v196, v67
	v_mov_b32_e32 v62, v67
	v_pk_add_f32 v[26:27], v[34:35], -1.0 op_sel_hi:[1,0]
	v_pk_add_f32 v[30:31], v[58:59], -1.0 op_sel_hi:[1,0]
	v_pk_fma_f32 v[26:27], v[54:55], v[26:27], 1.0 op_sel_hi:[1,1,0]
	v_pk_fma_f32 v[30:31], v[52:53], v[30:31], 1.0 op_sel_hi:[1,1,0]
	v_mov_b32_e32 v66, 0
	s_nop 0
	v_lshlrev_b32_e32 v52, 16, v198
	v_and_b32_e32 v53, 0xffff0000, v198
	v_lshlrev_b32_e32 v54, 16, v199
	v_and_b32_e32 v55, 0xffff0000, v199
	s_nop 0
	v_lshlrev_b32_e32 v198, 16, v200
	v_and_b32_e32 v199, 0xffff0000, v200
	v_lshlrev_b32_e32 v200, 16, v201
	v_and_b32_e32 v201, 0xffff0000, v201
	v_sub_f32_e32 v145, v145, v53
	v_sub_f32_e32 v144, v144, v52
	v_sub_f32_e32 v61, v147, v55
	v_sub_f32_e32 v60, v146, v54
	v_sub_f32_e32 v147, v151, v201
	v_sub_f32_e32 v146, v150, v200
	v_sub_f32_e32 v149, v149, v199
	v_sub_f32_e32 v148, v148, v198
	v_pk_fma_f32 v[60:61], v[46:47], v[60:61], v[54:55]
	v_pk_fma_f32 v[144:145], v[44:45], v[144:145], v[52:53]
	v_pk_fma_f32 v[44:45], v[48:49], v[148:149], v[198:199]
	v_pk_fma_f32 v[46:47], v[50:51], v[146:147], v[200:201]
	v_pk_mul_f32 v[36:37], v[36:37], v[44:45]
	v_pk_mul_f32 v[38:39], v[38:39], v[46:47]
	v_pk_mul_f32 v[26:27], v[26:27], v[46:47]
	v_pk_mul_f32 v[30:31], v[30:31], v[44:45]
	v_pk_mul_f32 v[44:45], v[38:39], v[38:39]
	v_pk_mul_f32 v[46:47], v[36:37], v[36:37]
	v_pk_mul_f32 v[48:49], v[144:145], v[30:31]
	v_pk_mul_f32 v[50:51], v[60:61], v[26:27]
	v_pk_mov_b32 v[52:53], v[46:47], v[44:45] op_sel:[1,0]
	v_mov_b32_e32 v47, v45
	v_pk_mul_f32 v[42:43], v[42:43], v[50:51]
	v_pk_mul_f32 v[40:41], v[40:41], v[48:49]
	v_pk_add_f32 v[44:45], v[52:53], v[46:47]
	v_add_f32_e32 v40, v40, v41
	v_add_f32_e32 v41, v42, v43
	v_add_f32_e32 v42, v44, v45
	v_add_f32_e32 v40, v40, v41
	s_nop 0
	v_add_f32_dpp v41, v42, v42 quad_perm:[1,0,3,2] row_mask:0xf bank_mask:0xf bound_ctrl:1
	v_add_f32_dpp v40, v40, v40 quad_perm:[1,0,3,2] row_mask:0xf bank_mask:0xf bound_ctrl:1
	s_nop 0
	v_add_f32_dpp v41, v41, v41 quad_perm:[2,3,0,1] row_mask:0xf bank_mask:0xf bound_ctrl:1
	v_add_f32_dpp v42, v40, v40 quad_perm:[2,3,0,1] row_mask:0xf bank_mask:0xf bound_ctrl:1
	s_nop 0
	v_add_f32_dpp v40, v41, v41 row_half_mirror row_mask:0xf bank_mask:0xf bound_ctrl:1
	v_add_f32_dpp v41, v42, v42 row_half_mirror row_mask:0xf bank_mask:0xf bound_ctrl:1
	s_nop 0
	v_mov_b32_dpp v196, v40 row_mirror row_mask:0xf bank_mask:0xf
	v_mov_b32_dpp v62, v41 row_mirror row_mask:0xf bank_mask:0xf
	s_and_saveexec_b64 s[2:3], s[24:25]
	s_cbranch_execz .LBB0_343
	v_ashrrev_i32_e32 v153, 31, v152
	v_lshlrev_b64 v[42:43], 6, v[152:153]
	v_lshl_add_u64 v[42:43], s[26:27], 0, v[42:43]
	v_add_f32_e32 v41, v41, v62
	v_mov_b32_e32 v66, 1.0
	global_store_dword v[42:43], v41, off sc1

; __device__ __forceinline__ void rw_chunk_prep(const Args& a, int head, int tc0, const LAS bf16* TDr, const LAS bf16* DAr, LAS unsigned char* lw_, int lane) {
;     ...
;         for (int i = 0; i < 4; ++i) { const f32x4 ei = exp4(lci[i]), eo = exp4(-lci[i]), ee = exp4(lci[i] - lw[i]), eh = exp4(ltot - lci[i]);
;             at[i] = av[i] * ee; rt[i] = rr[i] * ei; bh[i] = bv[i] * eh; kh[i] = km[i] * eh;
;             const int row = 4 * rg + i;
;             *(LAS v2u*)(TA + row * 64 + 4 * j) = pk4(at[i]); *(LAS v2u*)(TR + row * 64 + 4 * j) = pk4(rt[i]); *(LAS v2u*)(TB + row * 64 + 4 * j) = pk4(bv[i] * eo); *(LAS v2u*)(TK + row * 64 + 4 * j) = pk4(km[i] * eo); }
; #pragma unroll
;         for (int cb = 0; cb < 4; ++cb) { atT[cb] = (f32x4){at[0][cb], at[1][cb], at[2][cb], at[3][cb]}; rtT[cb] = (f32x4){rt[0][cb], rt[1][cb], rt[2][cb], rt[3][cb]};
;             bhT[cb] = (f32x4){bh[0][cb], bh[1][cb], bh[2][cb], bh[3][cb]}; khT[cb] = (f32x4){kh[0][cb], kh[1][cb], kh[2][cb], kh[3][cb]}; vT[cb] = (f32x4){vv[0][cb], vv[1][cb], vv[2][cb], vv[3][cb]}; }
;     }
;     LDS_WAIT(); asm volatile("" ::: "memory");
;     f32x4 AabT = {0.f, 0.f, 0.f, 0.f}, AakT = AabT, ArbT = AabT, ArkT = AabT;
; #pragma unroll
;     for (int kk = 0; kk < 2; ++kk) { const int o = j * 64 + kk * 32 + kg * 8;
;         const bf16x8 pa = *(const LAS bf16x8*)(TA + o), pr = *(const LAS bf16x8*)(TR + o), pb = *(const LAS bf16x8*)(TB + o), pk = *(const LAS bf16x8*)(TK + o);
;         AabT = MFMA32(pb, pa, AabT); AakT = MFMA32(pk, pa, AakT); ArbT = MFMA32(pb, pr, ArbT); ArkT = MFMA32(pk, pr, ArkT); }
; #pragma unroll
;     for (int e = 0; e < 4; ++e) { const int jp = 4 * rg + e; if (!(jp < j)) { AabT[e] = 0.f; AakT[e] = 0.f; } if (!(jp <= j)) { ArbT[e] = 0.f; ArkT[e] = 0.f; } }
;     *(LAS f32x4*)(MA + j * 16 + 4 * rg) = AabT;
;     LDS_WAIT(); asm volatile("" ::: "memory");
;     {   float x[16];
; #pragma unroll
;         for (int t = 0; t < 16; ++t) { float s = (t == j) ? 1.f : 0.f;
; #pragma unroll
;             for (int q = 0; q < 4; ++q) { if (4 * q < t) { const f32x4 row = *(const LAS f32x4*)(MA + t * 16 + 4 * q);
; #pragma unroll
;                 for (int e = 0; e < 4; ++e) if (4 * q + e < t) s += row[e] * x[4 * q + e]; } }
;             x[t] = s; }
;         if (rg == 0) {
; #pragma unroll
;             for (int t = 0; t < 16; ++t) MT[t * 16 + j] = x[t]; }
;     }
.LBB0_345:
	s_or_b64 exec, exec, s[26:27]
	s_waitcnt lgkmcnt(1)
	v_sub_f32_e32 v16, v132, v143
	v_sub_f32_e32 v17, v134, v142
	v_sub_f32_e32 v19, v133, v140
	v_sub_f32_e32 v18, v135, v141
	v_mul_f32_e32 v19, 0x3fb8aa3b, v19
	v_mul_f32_e32 v17, 0x3fb8aa3b, v17
	v_mul_f32_e32 v16, 0x3fb8aa3b, v16
	v_exp_f32_e32 v140, v19
	v_mul_f32_e32 v66, 0x3fb8aa3b, v18
	v_exp_f32_e32 v18, v17
	v_exp_f32_e32 v19, v16
	v_exp_f32_e32 v141, v66
	v_sub_f32_e32 v66, v132, v139
	v_sub_f32_e32 v136, v133, v136
	v_pk_mul_f32 v[16:17], v[118:119], v[18:19]
	v_sub_f32_e32 v118, v134, v138
	v_sub_f32_e32 v119, v135, v137
	v_mul_f32_e32 v136, 0x3fb8aa3b, v136
	v_mul_f32_e32 v119, 0x3fb8aa3b, v119
	v_mul_f32_e32 v118, 0x3fb8aa3b, v118
	v_mul_f32_e32 v66, 0x3fb8aa3b, v66
	v_exp_f32_e32 v136, v136
	v_exp_f32_e32 v138, v118
	v_exp_f32_e32 v139, v66
	v_exp_f32_e32 v137, v119
	v_pk_mul_f32 v[18:19], v[100:101], v[18:19]
	v_sub_f32_e32 v66, v132, v131
	v_pk_mul_f32 v[100:101], v[126:127], v[138:139]
	v_pk_mul_f32 v[118:119], v[124:125], v[136:137]
	v_sub_f32_e32 v124, v134, v130
	v_sub_f32_e32 v125, v135, v129
	v_sub_f32_e32 v126, v133, v128
	v_mul_f32_e32 v126, 0x3fb8aa3b, v126
	v_mul_f32_e32 v125, 0x3fb8aa3b, v125
	v_mul_f32_e32 v124, 0x3fb8aa3b, v124
	v_mul_f32_e32 v66, 0x3fb8aa3b, v66
	v_exp_f32_e32 v126, v126
	v_exp_f32_e32 v128, v124
	v_exp_f32_e32 v129, v66
	v_exp_f32_e32 v127, v125
	v_sub_f32_e32 v66, v135, v113
	v_sub_f32_e32 v112, v133, v112
	v_mul_f32_e32 v112, 0x3fb8aa3b, v112
	v_mul_f32_e32 v66, 0x3fb8aa3b, v66
	v_pk_mul_f32 v[124:125], v[28:29], v[136:137]
	v_pk_mul_f32 v[28:29], v[40:41], v[128:129]
	v_pk_mul_f32 v[40:41], v[38:39], v[126:127]
	v_sub_f32_e32 v38, v132, v115
	v_sub_f32_e32 v39, v134, v114
	v_exp_f32_e32 v112, v112
	v_exp_f32_e32 v113, v66
	v_mul_f32_e32 v39, 0x3fb8aa3b, v39
	v_mul_f32_e32 v38, 0x3fb8aa3b, v38
	v_mov_b32_e32 v66, s1
	v_exp_f32_e32 v114, v39
	v_exp_f32_e32 v115, v38
	v_pk_mul_f32 v[38:39], v[56:57], v[128:129]
	v_pk_mul_f32 v[56:57], v[104:105], v[126:127]
	v_mov_b32_e32 v104, s1
	v_cndmask_b32_e64 v66, v8, v66, s[10:11]
	v_pk_mul_f32 v[24:25], v[24:25], v[138:139]
	v_cndmask_b32_e64 v104, v12, v104, s[10:11]
	v_cndmask_b32_e64 v138, 0, v9, s[8:9]
	v_cndmask_b32_e64 v66, v66, v8, s[8:9]
	v_cndmask_b32_e64 v139, v10, 0, s[12:13]
	v_cndmask_b32_e64 v142, v11, 0, s[16:17]
	v_lshlrev_b32_e32 v8, 16, v32
	v_and_b32_e32 v9, 0xffff0000, v32
	s_waitcnt vmcnt(0)
	v_lshlrev_b32_e32 v10, 16, v106
	v_and_b32_e32 v11, 0xffff0000, v106
	v_pk_mul_f32 v[116:117], v[116:117], v[140:141]
	v_pk_mul_f32 v[102:103], v[102:103], v[140:141]
	v_pk_mul_f32 v[36:37], v[36:37], v[112:113]
	v_pk_mul_f32 v[30:31], v[30:31], v[112:113]
	v_cndmask_b32_e64 v112, 0, v13, s[8:9]
	v_cndmask_b32_e64 v113, v104, v12, s[8:9]
	v_cndmask_b32_e64 v137, 0, v7, s[14:15]
	v_cndmask_b32_e64 v140, 0, v6, s[20:21]
	v_cndmask_b32_e64 v136, 0, v5, s[22:23]
	v_cndmask_b32_e32 v141, 0, v4, vcc
	v_lshlrev_b32_e32 v6, 16, v33
	v_and_b32_e32 v7, 0xffff0000, v33
	v_lshlrev_b32_e32 v4, 16, v107
	v_and_b32_e32 v5, 0xffff0000, v107
	v_sub_f32_e32 v13, v9, v11
	v_sub_f32_e32 v12, v8, v10
	v_cndmask_b32_e64 v143, v14, 0, s[12:13]
	v_cndmask_b32_e64 v144, v15, 0, s[16:17]
	v_sub_f32_e32 v15, v7, v5
	v_sub_f32_e32 v14, v6, v4
	v_pk_fma_f32 v[32:33], v[0:1], v[12:13], v[10:11]
	v_lshlrev_b32_e32 v10, 16, v99
	v_and_b32_e32 v11, 0xffff0000, v99
	v_pk_fma_f32 v[4:5], v[2:3], v[14:15], v[4:5]
	v_lshlrev_b32_e32 v14, 16, v98
	v_and_b32_e32 v15, 0xffff0000, v98
	v_sub_f32_e32 v99, v11, v7
	v_sub_f32_e32 v98, v10, v6
	v_sub_f32_e32 v13, v15, v9
	v_sub_f32_e32 v12, v14, v8
	v_pk_fma_f32 v[6:7], v[2:3], v[98:99], v[6:7]
	v_lshlrev_b32_e32 v98, 16, v96
	v_and_b32_e32 v99, 0xffff0000, v96
	v_lshlrev_b32_e32 v96, 16, v97
	v_and_b32_e32 v97, 0xffff0000, v97
	s_waitcnt lgkmcnt(0)
	v_pk_mul_f32 v[34:35], v[34:35], v[114:115]
	v_pk_mul_f32 v[26:27], v[26:27], v[114:115]
	v_pk_fma_f32 v[114:115], v[0:1], v[12:13], v[8:9]
	v_sub_f32_e32 v9, v97, v11
	v_sub_f32_e32 v8, v96, v10
	v_pk_fma_f32 v[8:9], v[2:3], v[8:9], v[10:11]
	ds_read_b128 v[10:13], v166 offset:17408
	v_cvt_pk_bf16_f32 v136, v141, v136
	v_cvt_pk_bf16_f32 v137, v140, v137
	v_sub_f32_e32 v105, v99, v15
	v_sub_f32_e32 v104, v98, v14
	s_waitcnt lgkmcnt(0)
	v_cvt_pk_bf16_f32 v10, v10, v11
	v_cvt_pk_bf16_f32 v11, v12, v13
	v_pk_fma_f32 v[126:127], v[0:1], v[104:105], v[14:15]
	v_sub_f32_e32 v105, v188, v99
	v_sub_f32_e32 v104, v186, v98
	v_sub_f32_e32 v15, v189, v97
	v_sub_f32_e32 v14, v187, v96
	v_pk_fma_f32 v[128:129], v[0:1], v[104:105], v[98:99]
	v_pk_fma_f32 v[130:131], v[2:3], v[14:15], v[96:97]
	v_cvt_pk_bf16_f32 v2, v48, v58
	v_cvt_pk_bf16_f32 v3, v110, v122
	v_cvt_pk_bf16_f32 v140, v128, v126
	v_cvt_pk_bf16_f32 v141, v114, v32
	v_mfma_f32_16x16x16_bf16 v[12:15], v[10:11], v[2:3], 0
	v_cvt_pk_bf16_f32 v104, v46, v54
	v_cvt_pk_bf16_f32 v105, v108, v120
	v_cvt_pk_bf16_f32 v138, v66, v138
	v_mfma_f32_16x16x16_bf16 v[96:99], v[136:137], v[140:141], 0
	v_cvt_pk_bf16_f32 v139, v139, v142
	s_nop 2
	v_cvt_pk_bf16_f32 v106, v12, v13
	v_cvt_pk_bf16_f32 v107, v14, v15
	v_mfma_f32_16x16x16_bf16 v[12:15], v[104:105], v[78:79], 0
	v_cvt_pk_bf16_f32 v48, v49, v59
	v_cvt_pk_bf16_f32 v96, v96, v97
	v_cvt_pk_bf16_f32 v97, v98, v99
	v_cvt_pk_bf16_f32 v58, v129, v127
	v_cvt_pk_bf16_f32 v59, v115, v33
	v_mfma_f32_16x16x16_bf16 v[96:99], v[10:11], v[96:97], 0
	v_cvt_pk_bf16_f32 v49, v111, v123
	v_cvt_pk_bf16_f32 v142, v113, v112
	v_cvt_pk_bf16_f32 v143, v143, v144
	v_mfma_f32_16x16x16_bf16 v[126:129], v[136:137], v[58:59], 0
	v_cvt_pk_bf16_f32 v54, v47, v55
	s_nop 2
	v_cvt_pk_bf16_f32 v144, v96, v97
	v_cvt_pk_bf16_f32 v145, v98, v99
; __device__ __forceinline__ v2u pk4(f32x4 v) { v2u o; o.x = pk2(v.x, v.y); o.y = pk2(v.z, v.w); return o; }
; __device__ __forceinline__ bf16x4s pk4s(f32x4 v) { return __builtin_bit_cast(bf16x4s, pk4(v)); }
; __device__ __forceinline__ bf16x8 pk8s(f32x4 a, f32x4 b) { v4u u; u.x = pk2(a.x, a.y); u.y = pk2(a.z, a.w); u.z = pk2(b.x, b.y); u.w = pk2(b.z, b.w); return __builtin_bit_cast(bf16x8, u); }
; #define MFMA16(a, b, c) __builtin_amdgcn_mfma_f32_16x16x16bf16_1k(a, b, c, 0, 0, 0)
; __device__ __forceinline__ f32x4 exp4(f32x4 x) { return (f32x4){__expf(x.x), __expf(x.y), __expf(x.z), __expf(x.w)}; }
; __device__ __forceinline__ void rw_chunk_prep(const Args& a, int head, int tc0, const LAS bf16* TDr, const LAS bf16* DAr, LAS unsigned char* lw_, int lane) {
;     ...
;     const size_t ch = (size_t)(tc0 >> 4) * 16 + head;
;     unsigned char* outb = (unsigned char*)a.out;
;     f32x4 W1T[4], QT[4];
; #pragma unroll
;     for (int cb = 0; cb < 4; ++cb) {
;         const bf16x4s atp = pk4s(atT[cb]), vtp = pk4s(vT[cb]);
;         const f32x4 W1 = MFMA16(TmA, atp, z4);
;         W1T[cb] = MFMA16(atp, TmA, z4);
;         const f32x4 X = MFMA16(aak, vtp, z4);
;         const f32x4 U0 = MFMA16(TmA, pk4s(X), z4);
;         f32x4 q = MFMA16(pk4s(rtT[cb]), idb, z4);
;         QT[cb] = MFMA16(pk4s(W1), arb, q);
;         f32x4 y0 = MFMA16(arb, pk4s(U0), z4); y0 = MFMA16(ark, vtp, y0);
;         *(v2u*)(ws + WS_U0 + ch * 2048 + cb * 512 + lane * 8) = pk4(U0);
;         *(v2u*)(ws + WS_Y0 + ch * 2048 + cb * 512 + lane * 8) = pk4(y0);
;         *(v2u*)(outb + OUT_BT + ch * 2048 + cb * 512 + lane * 8) = pk4(bhT[cb]);
;         *(v2u*)(outb + OUT_KT + ch * 2048 + cb * 512 + lane * 8) = pk4(khT[cb]);
;         *(v2u*)(ws + WS_VS + ch * 2048 + cb * 512 + lane * 8) = pk4(vT[cb]);
;     }
; #pragma unroll
;     for (int kk = 0; kk < 2; ++kk) { *(bf16x8*)(outb + OUT_W1A + ch * 2048 + kk * 1024 + lane * 16) = pk8s(W1T[2 * kk], W1T[2 * kk + 1]); *(bf16x8*)(outb + OUT_QA + ch * 2048 + kk * 1024 + lane * 16) = pk8s(QT[2 * kk], QT[2 * kk + 1]); }
;     if (rg == 0) { float* dd = (float*)(ws + WS_DD) + ch * 64; const f32x4 dv = exp4(ltot);
; #pragma unroll
;         for (int cb = 0; cb < 4; ++cb) dd[((j >> 2) * 4 + cb) * 4 + (j & 3)] = dv[cb]; }
	v_mfma_f32_16x16x16_bf16 v[12:15], v[106:107], v[138:139], v[12:15]
	v_cvt_pk_bf16_f32 v55, v109, v121
	v_cvt_pk_bf16_f32 v32, v126, v127
	v_cvt_pk_bf16_f32 v33, v128, v129
	v_mfma_f32_16x16x16_bf16 v[104:107], v[10:11], v[48:49], 0
	s_ashr_i32 s2, s60, 4
	s_ashr_i32 s3, s2, 31
	s_lshl_b64 s[2:3], s[2:3], 4
	v_mfma_f32_16x16x16_bf16 v[96:99], v[138:139], v[144:145], 0
	v_cvt_pk_bf16_f32 v114, v22, v44
	v_cvt_pk_bf16_f32 v115, v52, v62
	s_add_u32 s2, s2, s0
	v_mfma_f32_16x16x16_bf16 v[110:113], v[48:49], v[10:11], 0
	s_addc_u32 s3, s3, 0
	s_lshl_b64 s[26:27], s[2:3], 11
	v_lshl_add_u64 v[148:149], v[82:83], 0, s[26:27]
	v_mfma_f32_16x16x16_bf16 v[46:49], v[10:11], v[32:33], 0
	v_cvt_pk_bf16_f32 v32, v104, v105
	v_cvt_pk_bf16_f32 v33, v106, v107
	v_lshl_add_u64 v[146:147], v[80:81], 0, s[26:27]
	v_mfma_f32_16x16x16_bf16 v[96:99], v[142:143], v[140:141], v[96:99]
	v_lshl_add_u64 v[150:151], v[84:85], 0, s[26:27]
	v_lshl_add_u64 v[152:153], v[86:87], 0, s[26:27]
	global_store_dwordx2 v[146:147], v[144:145], off sc1
	v_mfma_f32_16x16x16_bf16 v[104:107], v[54:55], v[78:79], 0
	v_lshl_add_u64 v[108:109], v[88:89], 0, s[26:27]
	s_nop 2
	v_cvt_pk_bf16_f32 v54, v96, v97
	v_cvt_pk_bf16_f32 v55, v98, v99
	v_mfma_f32_16x16x16_bf16 v[96:99], v[32:33], v[138:139], v[104:107]
	v_cvt_pk_bf16_f32 v32, v46, v47
	v_cvt_pk_bf16_f32 v33, v48, v49
	global_store_dwordx2 v[148:149], v[54:55], off sc1
	v_cvt_pk_bf16_f32 v54, v116, v118
	v_mfma_f32_16x16x16_bf16 v[46:49], v[138:139], v[32:33], 0
	v_cvt_pk_bf16_f32 v55, v40, v36
	global_store_dwordx2 v[150:151], v[54:55], off sc1
	v_cvt_pk_bf16_f32 v54, v102, v124
	v_mfma_f32_16x16x16_bf16 v[104:107], v[10:11], v[114:115], 0
	v_cvt_pk_bf16_f32 v55, v56, v30
	global_store_dwordx2 v[152:153], v[54:55], off sc1
	global_store_dwordx2 v[108:109], v[140:141], off sc1
	v_cvt_pk_bf16_f32 v54, v20, v42
	v_mfma_f32_16x16x16_bf16 v[120:123], v[114:115], v[10:11], 0
	v_cvt_pk_bf16_f32 v114, v130, v8
	v_cvt_pk_bf16_f32 v115, v6, v4
	v_cvt_pk_bf16_f32 v55, v50, v60
	v_mfma_f32_16x16x16_bf16 v[46:49], v[142:143], v[58:59], v[46:49]
	global_store_dwordx2 v[146:147], v[32:33], off offset:512 sc1
	v_cvt_pk_bf16_f32 v22, v23, v45
	v_cvt_pk_bf16_f32 v23, v53, v63
	v_mfma_f32_16x16x16_bf16 v[126:129], v[136:137], v[114:115], 0
	v_cvt_pk_bf16_f32 v40, v103, v125
	v_cvt_pk_bf16_f32 v8, v21, v43
	v_mfma_f32_16x16x16_bf16 v[0:3], v[2:3], v[10:11], 0
	s_nop 4
	v_cvt_pk_bf16_f32 v32, v126, v127
	v_cvt_pk_bf16_f32 v33, v128, v129
	s_nop 0
	v_cvt_pk_bf16_f32 v0, v0, v1
	v_cvt_pk_bf16_f32 v1, v2, v3
	v_mfma_f32_16x16x16_bf16 v[126:129], v[10:11], v[32:33], 0
	v_cvt_pk_bf16_f32 v32, v46, v47
	v_cvt_pk_bf16_f32 v46, v104, v105
	v_cvt_pk_bf16_f32 v47, v106, v107
	v_mfma_f32_16x16x16_bf16 v[104:107], v[54:55], v[78:79], 0
	v_cvt_pk_bf16_f32 v33, v48, v49
	global_store_dwordx2 v[148:149], v[32:33], off offset:512 sc1
	v_cvt_pk_bf16_f32 v32, v117, v119
	v_cvt_pk_bf16_f32 v33, v41, v37
	v_cvt_pk_bf16_f32 v36, v126, v127
	v_cvt_pk_bf16_f32 v37, v128, v129
	v_cvt_pk_bf16_f32 v41, v57, v31
	v_mfma_f32_16x16x16_bf16 v[46:49], v[46:47], v[138:139], v[104:107]
	global_store_dwordx2 v[150:151], v[32:33], off offset:512 sc1
	global_store_dwordx2 v[152:153], v[40:41], off offset:512 sc1
	global_store_dwordx2 v[108:109], v[58:59], off offset:512 sc1
	global_store_dwordx2 v[146:147], v[36:37], off offset:1024 sc1
	v_mfma_f32_16x16x16_bf16 v[104:107], v[138:139], v[36:37], 0
	v_cvt_pk_bf16_f32 v2, v110, v111
	v_cvt_pk_bf16_f32 v3, v112, v113
	v_mfma_f32_16x16x16_bf16 v[52:55], v[10:11], v[22:23], 0
	v_mfma_f32_16x16x16_bf16 v[56:59], v[22:23], v[10:11], 0
	v_cvt_pk_bf16_f32 v22, v131, v9
	v_cvt_pk_bf16_f32 v23, v7, v5
	v_cvt_pk_bf16_f32 v9, v51, v61
	v_mfma_f32_16x16x16_bf16 v[30:33], v[142:143], v[114:115], v[104:107]
	s_nop 2
	v_cvt_pk_bf16_f32 v20, v52, v53
	v_cvt_pk_bf16_f32 v21, v54, v55
	v_mfma_f32_16x16x16_bf16 v[4:7], v[136:137], v[22:23], 0
	s_nop 1
	v_cvt_pk_bf16_f32 v30, v30, v31
	s_nop 4
	v_cvt_pk_bf16_f32 v4, v4, v5
	v_cvt_pk_bf16_f32 v5, v6, v7
	v_cvt_pk_bf16_f32 v31, v32, v33
	global_store_dwordx2 v[148:149], v[30:31], off offset:1024 sc1
	v_mfma_f32_16x16x16_bf16 v[4:7], v[10:11], v[4:5], 0
	v_cvt_pk_bf16_f32 v30, v16, v100
	v_cvt_pk_bf16_f32 v31, v28, v34
	global_store_dwordx2 v[150:151], v[30:31], off offset:1024 sc1
	v_mfma_f32_16x16x16_bf16 v[8:11], v[8:9], v[78:79], 0
	v_mfma_f32_16x16x16_bf16 v[8:11], v[20:21], v[138:139], v[8:11]
	s_nop 2
	v_cvt_pk_bf16_f32 v30, v4, v5
	v_cvt_pk_bf16_f32 v31, v6, v7
	v_cvt_pk_bf16_f32 v20, v18, v24
	v_cvt_pk_bf16_f32 v21, v38, v26
	v_mfma_f32_16x16x16_bf16 v[4:7], v[138:139], v[30:31], 0
	global_store_dwordx2 v[152:153], v[20:21], off offset:1024 sc1
	global_store_dwordx2 v[108:109], v[114:115], off offset:1024 sc1
	global_store_dwordx2 v[146:147], v[30:31], off offset:1536 sc1
	v_mfma_f32_16x16x16_bf16 v[4:7], v[142:143], v[22:23], v[4:7]
	s_nop 7
	v_cvt_pk_bf16_f32 v4, v4, v5
	v_cvt_pk_bf16_f32 v5, v6, v7
	global_store_dwordx2 v[148:149], v[4:5], off offset:1536 sc1
	v_cvt_pk_bf16_f32 v4, v17, v101
	v_cvt_pk_bf16_f32 v5, v29, v35
	global_store_dwordx2 v[150:151], v[4:5], off offset:1536 sc1
	v_cvt_pk_bf16_f32 v4, v19, v25
	v_cvt_pk_bf16_f32 v5, v39, v27
	global_store_dwordx2 v[152:153], v[4:5], off offset:1536 sc1
	global_store_dwordx2 v[108:109], v[22:23], off offset:1536 sc1
	v_lshl_add_u64 v[4:5], v[90:91], 0, s[26:27]
	v_lshl_add_u64 v[6:7], v[92:93], 0, s[26:27]
	global_store_dwordx4 v[4:5], v[0:3], off sc1
	s_nop 1
	v_cvt_pk_bf16_f32 v0, v12, v13
	v_cvt_pk_bf16_f32 v1, v14, v15
	v_cvt_pk_bf16_f32 v2, v96, v97
	v_cvt_pk_bf16_f32 v3, v98, v99
	global_store_dwordx4 v[6:7], v[0:3], off sc1
	s_nop 1
	v_cvt_pk_bf16_f32 v0, v120, v121
	v_cvt_pk_bf16_f32 v1, v122, v123
	v_cvt_pk_bf16_f32 v2, v56, v57
	v_cvt_pk_bf16_f32 v3, v58, v59
	global_store_dwordx4 v[4:5], v[0:3], off offset:1024 sc1
	s_nop 1
	v_cvt_pk_bf16_f32 v0, v46, v47
	v_cvt_pk_bf16_f32 v1, v48, v49
	v_cvt_pk_bf16_f32 v2, v8, v9
	v_cvt_pk_bf16_f32 v3, v10, v11
	global_store_dwordx4 v[6:7], v[0:3], off offset:1024 sc1
	s_and_saveexec_b64 s[26:27], s[18:19]
	s_cbranch_execz .LBB0_328
	v_mul_f32_e32 v0, 0x3fb8aa3b, v133
	v_exp_f32_e32 v0, v0
	v_mul_f32_e32 v1, 0x3fb8aa3b, v135
	v_mul_f32_e32 v3, 0x3fb8aa3b, v132
	s_lshl_b64 s[2:3], s[2:3], 8
	v_exp_f32_e32 v1, v1
	v_mul_f32_e32 v2, 0x3fb8aa3b, v134
	v_exp_f32_e32 v3, v3
	s_add_u32 s2, s37, s2
	v_exp_f32_e32 v2, v2
	s_addc_u32 s3, s40, s3
	global_store_dword v183, v0, s[2:3] sc1
	global_store_dword v183, v1, s[2:3] offset:16 sc1
	global_store_dword v183, v2, s[2:3] offset:32 sc1
	v_lshl_add_u64 v[0:1], v[94:95], 2, s[2:3]
	global_store_dword v[0:1], v3, off sc1
	s_branch .LBB0_328
